# hgrn1: explicit wait for the next-unit prefetch before the loop-carried register copies (closes a latent race of the counted-wait edit)
# speedup vs baseline: 1.0068x; 1.0010x over previous
; #define LAS __attribute__((address_space(3)))
; DI float shx_(int lane, float v, int m) { return __builtin_bit_cast(float, __builtin_amdgcn_ds_bpermute((lane ^ m) << 2, __builtin_bit_cast(int, v))); }
; #define MFMA32(a, b, c) __builtin_amdgcn_mfma_f32_32x32x16_bf16((a), (b), (c), 0, 0, 0)
; template <int MODE> DI void hgrn_chunk_phase(const Args& A, int wave_s, int l, bool need_ctx, LAS unsigned char* lds) {
;     ...
; #pragma unroll
;             for (int ks = 0; ks < 4; ++ks) { const bf16x8 a = tr_nat(SP, 16 * ks, 32 * mt, lane), bq = *(LAS bf16x8*)(QQ + (32 * tblk + r) * KV_PITCH + ks * 32 + h5 * 16); O = MFMA32(a, bq, O); }
;             const int pos = 32 * tblk + r, tloc = dir ? 63 - pos : pos;
; #pragma unroll
;             for (int i = 0; i < 16; ++i) { const int dv = 32 * mt + (i & 3) + 8 * (i >> 2) + 4 * h5; OX[(dir * 64 + tloc) * 68 + dv] = O[i]; }
;             __syncthreads();
;             {
;                 const int t = C.tid >> 3, part = C.tid & 7; const int row = rbase + t;
;                 float tot[8]; float ss = 0.f;
; #pragma unroll
;                 for (int e = 0; e < 8; ++e) { tot[e] = OX[t * 68 + part * 8 + e] + OX[(64 + t) * 68 + part * 8 + e]; ss += tot[e] * tot[e]; }
;                 ss += shx_(C.lane, ss, 1); ss += shx_(C.lane, ss, 2); ss += shx_(C.lane, ss, 4);
;                 const float rs = rsqrtf(ss * (1.f / 64.f) + EPS);
;                 const v4u gr = *(const v4u*)(C.P + (size_t)row * INW + CB_G + hd * 64 + part * 8);
.LBB0_383:
	s_waitcnt vmcnt(0)
	v_add_u32_e32 v130, s96, v61
	s_lshl_b32 s60, s58, 1
	s_mov_b32 s61, 0
	v_mov_b64_e32 v[128:129], s[84:85]
	v_mad_i64_i32 v[128:129], s[54:55], v130, s77, v[128:129]
	v_lshl_add_u64 v[128:129], v[128:129], 0, s[60:61]
	v_lshl_add_u64 v[128:129], v[128:129], 0, v[160:161]
	v_add_co_u32_e32 v128, vcc, s76, v128
	s_nop 1
	v_addc_co_u32_e32 v129, vcc, 0, v129, vcc
	global_load_dwordx4 v[132:135], v[128:129], off
	global_load_dwordx4 v[136:139], v[44:45], off offset:16
	global_load_dwordx4 v[140:143], v[44:45], off
	ds_read_b64_tr_b16 v[16:17], v70 offset:36864
	ds_read_b64_tr_b16 v[18:19], v70 offset:37440
	ds_read_b128 v[20:23], v72 offset:18432
	ds_read_b128 v[24:27], v72 offset:18464
	s_add_i32 s83, s83, s92
	s_sub_i32 s2, s2, s90
	v_mov_b32_e32 v43, v79
	s_waitcnt lgkmcnt(1)
	v_mfma_f32_32x32x16_bf16 v[0:15], v[16:19], v[20:23], v[0:15]
	ds_read_b64_tr_b16 v[16:17], v70 offset:39168
	ds_read_b64_tr_b16 v[18:19], v70 offset:39744
	v_mov_b32_e32 v41, v80
	v_mov_b32_e32 v40, v85
	v_mov_b32_e32 v42, v76
	v_mov_b32_e32 v106, v92
	s_mov_b32 s59, s95
	v_readlane_b32 s95, v255, 24
	s_waitcnt lgkmcnt(0)
	v_mfma_f32_32x32x16_bf16 v[0:15], v[16:19], v[24:27], v[0:15]
	ds_read_b64_tr_b16 v[16:17], v70 offset:41472
	ds_read_b64_tr_b16 v[18:19], v70 offset:42048
	ds_read_b128 v[20:23], v72 offset:18496
	s_waitcnt lgkmcnt(0)
	v_mfma_f32_32x32x16_bf16 v[0:15], v[16:19], v[20:23], v[0:15]
	ds_read_b64_tr_b16 v[16:17], v70 offset:43776
	ds_read_b64_tr_b16 v[18:19], v70 offset:44352
	ds_read_b128 v[20:23], v72 offset:18528
	s_waitcnt lgkmcnt(0)
	v_mfma_f32_32x32x16_bf16 v[0:15], v[16:19], v[20:23], v[0:15]
	v_add_u32_e32 v16, s96, v61
	s_lshl_b32 s96, s58, 1
	v_ashrrev_i32_e32 v17, 31, v16
	s_nop 8
	ds_write_b128 v66, v[0:3]
	ds_write_b128 v66, v[4:7] offset:32
	ds_write_b128 v66, v[8:11] offset:64
	ds_write_b128 v66, v[12:15] offset:96
	v_mov_b64_e32 v[0:1], s[84:85]
	v_mad_i64_i32 v[0:1], s[54:55], v16, s77, v[0:1]
	v_lshl_add_u64 v[0:1], v[0:1], 0, s[96:97]
	v_lshl_add_u64 v[0:1], v[0:1], 0, v[160:161]
	v_add_co_u32_e32 v0, vcc, s76, v0
	s_waitcnt lgkmcnt(0)
	s_nop 0
	v_addc_co_u32_e32 v1, vcc, 0, v1, vcc
	s_barrier
; DI float shx_(int lane, float v, int m) { return __builtin_bit_cast(float, __builtin_amdgcn_ds_bpermute((lane ^ m) << 2, __builtin_bit_cast(int, v))); }
; DI float silu_f(float x) { return x / (1.f + __expf(-x)); }
; DI unsigned pkbf(float a, float b) { fv2 v = {a, b}; return __builtin_bit_cast(unsigned, __builtin_convertvector(v, bfv2)); }
; template <int MODE> DI void hgrn_chunk_phase(const Args& A, int wave_s, int l, bool need_ctx, LAS unsigned char* lds) {
;     ...
;             {
;                 const int t = C.tid >> 3, part = C.tid & 7; const int row = rbase + t;
;                 float tot[8]; float ss = 0.f;
; #pragma unroll
;                 for (int e = 0; e < 8; ++e) { tot[e] = OX[t * 68 + part * 8 + e] + OX[(64 + t) * 68 + part * 8 + e]; ss += tot[e] * tot[e]; }
;                 ss += shx_(C.lane, ss, 1); ss += shx_(C.lane, ss, 2); ss += shx_(C.lane, ss, 4);
;                 const float rs = rsqrtf(ss * (1.f / 64.f) + EPS);
;                 const v4u gr = *(const v4u*)(C.P + (size_t)row * INW + CB_G + hd * 64 + part * 8);
;                 unsigned res[4];
; #pragma unroll
;                 for (int q = 0; q < 4; ++q) { const float g0 = __builtin_bit_cast(float, gr[q] << 16), g1 = __builtin_bit_cast(float, gr[q] & 0xffff0000u);
;                     const float y0 = tot[2 * q] * rs * C.hgog[l * 64 + part * 8 + 2 * q] * silu_f(g0), y1 = tot[2 * q + 1] * rs * C.hgog[l * 64 + part * 8 + 2 * q + 1] * silu_f(g1);
;                     res[q] = pkbf(y0, y1); }
;                 v4u o; o.x = res[0]; o.y = res[1]; o.z = res[2]; o.w = res[3];
;                 *(v4u*)(C.MIX + (size_t)row * 1024 + 512 + hd * 64 + part * 8) = o;
;             }
	s_nop 0
	ds_read_b128 v[12:15], v62
	ds_read_b128 v[4:7], v62 offset:16
	ds_read_b128 v[8:11], v62 offset:17424
	s_waitcnt lgkmcnt(0)
	v_pk_add_f32 v[20:21], v[4:5], v[8:9]
	v_pk_add_f32 v[18:19], v[6:7], v[10:11]
	v_pk_mul_f32 v[26:27], v[20:21], v[20:21]
	v_pk_mul_f32 v[24:25], v[18:19], v[18:19]
	s_waitcnt vmcnt(0)
	v_mov_b32_e32 v0, v132
	v_mov_b32_e32 v1, v133
	v_mov_b32_e32 v2, v134
	v_mov_b32_e32 v3, v135
	v_lshlrev_b32_e32 v28, 16, v2
	v_and_b32_e32 v2, 0xffff0000, v2
	v_mul_f32_e32 v4, 0xbfb8aa3b, v28
	v_mul_f32_e32 v23, 0xbfb8aa3b, v2
	v_exp_f32_e32 v22, v4
	v_exp_f32_e32 v23, v23
	v_mov_b32_e32 v4, v136
	v_mov_b32_e32 v5, v137
	v_mov_b32_e32 v6, v138
	v_mov_b32_e32 v7, v139
	v_mov_b32_e32 v8, v140
	v_mov_b32_e32 v9, v141
	v_mov_b32_e32 v10, v142
	v_mov_b32_e32 v11, v143
	v_pk_add_f32 v[22:23], v[22:23], 1.0 op_sel_hi:[1,0]
	s_nop 0
	v_div_scale_f32 v29, s[54:55], v23, v23, v2
	v_rcp_f32_e32 v30, v29
	s_nop 0
	v_fma_f32 v31, -v29, v30, 1.0
	v_fmac_f32_e32 v30, v31, v30
	v_div_scale_f32 v31, vcc, v2, v23, v2
	v_mul_f32_e32 v32, v31, v30
	v_fma_f32 v33, -v29, v32, v31
	v_fmac_f32_e32 v32, v33, v30
	v_fma_f32 v29, -v29, v32, v31
	v_div_fmas_f32 v29, v29, v30, v32
	v_div_fixup_f32 v23, v29, v23, v2
	v_div_scale_f32 v2, s[54:55], v22, v22, v28
	v_rcp_f32_e32 v29, v2
	s_nop 0
	v_fma_f32 v30, -v2, v29, 1.0
	v_fmac_f32_e32 v29, v30, v29
	v_div_scale_f32 v30, vcc, v28, v22, v28
	v_mul_f32_e32 v31, v30, v29
	v_fma_f32 v32, -v2, v31, v30
	v_fmac_f32_e32 v31, v32, v29
	v_fma_f32 v2, -v2, v31, v30
	v_div_fmas_f32 v2, v2, v29, v31
	v_div_fixup_f32 v22, v2, v22, v28
	v_lshlrev_b32_e32 v2, 16, v1
	v_and_b32_e32 v1, 0xffff0000, v1
	v_mul_f32_e32 v28, 0xbfb8aa3b, v2
	v_mul_f32_e32 v29, 0xbfb8aa3b, v1
	ds_read_b128 v[32:35], v62 offset:17408
	v_exp_f32_e32 v28, v28
	v_exp_f32_e32 v29, v29
	s_waitcnt lgkmcnt(0)
	v_pk_add_f32 v[14:15], v[14:15], v[34:35]
	v_pk_add_f32 v[28:29], v[28:29], 1.0 op_sel_hi:[1,0]
	v_pk_add_f32 v[12:13], v[12:13], v[32:33]
	v_div_scale_f32 v34, s[54:55], v29, v29, v1
	v_rcp_f32_e32 v35, v34
	v_pk_mul_f32 v[32:33], v[12:13], v[12:13]
	v_pk_mul_f32 v[30:31], v[14:15], v[14:15]
	v_fma_f32 v36, -v34, v35, 1.0
	v_fmac_f32_e32 v35, v36, v35
	v_div_scale_f32 v36, vcc, v1, v29, v1
	v_mul_f32_e32 v37, v36, v35
	v_fma_f32 v38, -v34, v37, v36
	v_fmac_f32_e32 v37, v38, v35
	v_fma_f32 v34, -v34, v37, v36
	v_div_fmas_f32 v34, v34, v35, v37
	v_div_fixup_f32 v29, v34, v29, v1
	v_div_scale_f32 v1, s[54:55], v28, v28, v2
	v_rcp_f32_e32 v34, v1
	s_nop 0
	v_fma_f32 v35, -v1, v34, 1.0
	v_fmac_f32_e32 v34, v35, v34
	v_div_scale_f32 v35, vcc, v2, v28, v2
	v_mul_f32_e32 v36, v35, v34
	v_fma_f32 v37, -v1, v36, v35
	v_fmac_f32_e32 v36, v37, v34
	v_fma_f32 v1, -v1, v36, v35
	v_div_fmas_f32 v1, v1, v34, v36
	v_div_fixup_f32 v28, v1, v28, v2
	v_lshlrev_b32_e32 v2, 16, v0
	v_and_b32_e32 v34, 0xffff0000, v0
	v_mul_f32_e32 v0, 0xbfb8aa3b, v2
	v_mul_f32_e32 v1, 0xbfb8aa3b, v34
	v_exp_f32_e32 v0, v0
	v_exp_f32_e32 v1, v1
	s_nop 0
	v_pk_add_f32 v[0:1], v[0:1], 1.0 op_sel_hi:[1,0]
	s_nop 0
	v_div_scale_f32 v35, s[54:55], v1, v1, v34
	v_rcp_f32_e32 v36, v35
	s_nop 0
	v_fma_f32 v37, -v35, v36, 1.0
	v_fmac_f32_e32 v36, v37, v36
	v_div_scale_f32 v37, vcc, v34, v1, v34
	v_mul_f32_e32 v38, v37, v36
	v_fma_f32 v39, -v35, v38, v37
	v_fmac_f32_e32 v38, v39, v36
	v_fma_f32 v35, -v35, v38, v37
	v_div_fmas_f32 v35, v35, v36, v38
	v_div_fixup_f32 v1, v35, v1, v34
	v_div_scale_f32 v34, s[54:55], v0, v0, v2
	v_rcp_f32_e32 v35, v34
	v_mov_b32_e32 v39, v78
	v_fma_f32 v36, -v34, v35, 1.0
	v_fmac_f32_e32 v35, v36, v35
	v_div_scale_f32 v36, vcc, v2, v0, v2
	v_mul_f32_e32 v37, v36, v35
	v_fma_f32 v38, -v34, v37, v36
	v_fmac_f32_e32 v37, v38, v35
	v_fma_f32 v34, -v34, v37, v36
	v_div_fmas_f32 v34, v34, v35, v37
	v_div_fixup_f32 v0, v34, v0, v2
	v_add_f32_e32 v2, v32, v33
	v_add_f32_e32 v2, v2, v30
	v_add_f32_e32 v2, v2, v31
	v_add_f32_e32 v2, v2, v26
	v_add_f32_e32 v2, v2, v27
	v_add_f32_e32 v2, v2, v24
	v_add_f32_e32 v2, v2, v25
	ds_bpermute_b32 v24, v63, v2
	v_mov_b32_e32 v27, v105
	v_mov_b32_e32 v26, v103
	v_mov_b32_e32 v37, v87
	v_mov_b32_e32 v36, v89
	s_waitcnt lgkmcnt(0)
	v_add_f32_e32 v2, v2, v24
	ds_bpermute_b32 v24, v64, v2
	v_mov_b32_e32 v33, v94
	v_mov_b32_e32 v32, v96
	v_mov_b32_e32 v38, v82
	v_mov_b32_e32 v35, v84
	s_waitcnt lgkmcnt(0)
	v_add_f32_e32 v2, v2, v24
	ds_bpermute_b32 v24, v65, v2
	v_mov_b32_e32 v34, v86
	v_mov_b32_e32 v31, v91
	v_mov_b32_e32 v30, v93
	s_waitcnt lgkmcnt(0)
	v_add_f32_e32 v2, v2, v24
	v_fmamk_f32 v2, v2, 0x3c800000, v162
	v_cmp_gt_f32_e32 vcc, s78, v2
	v_mul_f32_e32 v24, 0x4b800000, v2
	s_nop 0
	v_cndmask_b32_e32 v2, v2, v24, vcc
	v_rsq_f32_e32 v2, v2
	s_nop 0
	v_mul_f32_e32 v24, 0x45800000, v2
	v_cndmask_b32_e32 v24, v2, v24, vcc
	v_pk_mul_f32 v[12:13], v[12:13], v[24:25] op_sel_hi:[1,0]
	s_waitcnt vmcnt(0)
	v_pk_mul_f32 v[8:9], v[8:9], v[12:13]
	s_nop 0
	v_pk_mul_f32 v[0:1], v[0:1], v[8:9]
	v_pk_mul_f32 v[8:9], v[14:15], v[24:25] op_sel_hi:[1,0]
	v_cvt_pk_bf16_f32 v0, v0, v1
	v_pk_mul_f32 v[8:9], v[10:11], v[8:9]
	v_lshlrev_b32_e32 v10, 16, v3
	v_pk_mul_f32 v[8:9], v[28:29], v[8:9]
	v_and_b32_e32 v3, 0xffff0000, v3
	v_cvt_pk_bf16_f32 v1, v8, v9
	v_pk_mul_f32 v[8:9], v[20:21], v[24:25] op_sel_hi:[1,0]
	v_mov_b32_e32 v21, v100
	v_pk_mul_f32 v[4:5], v[4:5], v[8:9]
	v_pk_mul_f32 v[8:9], v[18:19], v[24:25] op_sel_hi:[1,0]
	v_pk_mul_f32 v[4:5], v[22:23], v[4:5]
	v_pk_mul_f32 v[6:7], v[6:7], v[8:9]
	v_cvt_pk_bf16_f32 v2, v4, v5
	v_mul_f32_e32 v4, 0xbfb8aa3b, v10
	v_mul_f32_e32 v5, 0xbfb8aa3b, v3
	v_exp_f32_e32 v4, v4
	v_exp_f32_e32 v5, v5
	v_mov_b32_e32 v25, v104
	v_mov_b32_e32 v23, v102
	v_mov_b32_e32 v24, v101
	v_pk_add_f32 v[4:5], v[4:5], 1.0 op_sel_hi:[1,0]
	v_mov_b32_e32 v22, v99
	v_div_scale_f32 v8, s[54:55], v5, v5, v3
	v_rcp_f32_e32 v9, v8
	v_mov_b32_e32 v20, v98
	v_mov_b32_e32 v29, v97
	v_mov_b32_e32 v28, v95
	v_fma_f32 v11, -v8, v9, 1.0
	v_fmac_f32_e32 v9, v11, v9
	v_div_scale_f32 v11, vcc, v3, v5, v3
	v_mul_f32_e32 v12, v11, v9
	v_fma_f32 v13, -v8, v12, v11
	v_fmac_f32_e32 v12, v13, v9
	v_fma_f32 v8, -v8, v12, v11
	v_div_fmas_f32 v8, v8, v9, v12
	v_div_fixup_f32 v5, v8, v5, v3
	v_div_scale_f32 v3, s[54:55], v4, v4, v10
	v_rcp_f32_e32 v8, v3
	s_nop 0
	v_fma_f32 v9, -v3, v8, 1.0
	v_fmac_f32_e32 v8, v9, v8
	v_div_scale_f32 v9, vcc, v10, v4, v10
	v_mul_f32_e32 v11, v9, v8
	v_fma_f32 v12, -v3, v11, v9
	v_fmac_f32_e32 v11, v12, v8
	v_fma_f32 v3, -v3, v11, v9
	v_div_fmas_f32 v3, v3, v8, v11
	v_div_fixup_f32 v4, v3, v4, v10
	v_pk_mul_f32 v[4:5], v[4:5], v[6:7]
	v_mov_b32_e32 v6, v77
	v_cvt_pk_bf16_f32 v3, v4, v5
	v_lshlrev_b64 v[4:5], 11, v[16:17]
	v_lshl_add_u64 v[4:5], s[88:89], 0, v[4:5]
	v_lshl_add_u64 v[4:5], v[4:5], 0, s[96:97]
	v_lshl_add_u64 v[4:5], v[4:5], 0, v[160:161]
	v_add_co_u32_e32 v4, vcc, 0x7a00000, v4
	v_mov_b32_e32 v8, v81
	s_nop 0
	v_addc_co_u32_e32 v5, vcc, 0, v5, vcc
	global_store_dwordx4 v[4:5], v[0:3], off offset:1024
	s_andn2_b64 vcc, exec, s[74:75]
	v_mov_b32_e32 v4, v75
	v_mov_b32_e32 v2, v74
	v_mov_b32_e32 v12, v83
	v_mov_b32_e32 v11, v88
	v_mov_b32_e32 v10, v90
	s_cbranch_vccz .LBB0_398
